# v21 plus the four v_mov_b64 of the attention common path as eight v_mov_b32
# baseline (speedup 1.0000x reference)
.LBB0_965:
	v_mov_b32_e32 v208, 1.0
	v_mov_b32_e32 v122, v50
	v_mov_b32_e32 v123, v51
	v_mov_b32_e32 v126, v54
	v_mov_b32_e32 v127, v55
	v_mov_b32_e32 v120, v48
	v_mov_b32_e32 v121, v49
	v_mov_b32_e32 v124, v52
	v_mov_b32_e32 v125, v53
	v_mov_b32_e32 v209, v208
